# G1 start skew 3us per group instead of 1us (v75 otherwise)
# baseline (speedup 1.0000x reference)
.Lskew_loop_g1:
	s_sleep 96
	s_sub_u32 s4, s4, 1
	s_cmp_lg_u32 s4, 0
	s_cbranch_scc1 .Lskew_loop_g1
